# mixer A dilated groups: removed the s_waitcnt vmcnt(0) right behind each group's query-row loads (first consumer sits behind the first tile's wait)
# speedup vs baseline: 1.0056x; 1.0056x over previous
.LBB0_617:
	v_lshrrev_b32_e32 v210, 3, v111
	v_lshl_add_u32 v210, v112, 1, v210
	v_and_b32_e32 v211, 7, v111
	v_lshlrev_b32_e32 v208, 4, v211
	v_mov_b32_e32 v209, v137
	v_lshlrev_b32_e32 v212, 3, v211
	v_mov_b32_e32 v213, v137
	v_mov_b32_e32 v214, 0x10000
	v_mov_b32_e32 v215, v137
	v_mov_b32_e32 v232, 0x1000
	v_mov_b32_e32 v233, v137
	s_mov_b32 s100, 0
	s_nop 0
	v_writelane_b32 v255, s100, 61
	v_readlane_b32 s100, v255, 8
	s_nop 0
	s_mul_i32 s100, s100, 0x280
	s_add_i32 s100, s100, 0x4000
	v_mul_u32_u24_e32 v234, 0xa0, v210
	v_lshl_add_u32 v234, v211, 4, v234
	v_add_u32_e32 v234, s100, v234
	v_mul_u32_u24_e32 v235, 0xa0, v111
	v_lshl_add_u32 v235, v112, 4, v235
	v_add_u32_e32 v235, s100, v235
	s_ashr_i32 s6, s45, 2
	s_max_i32 s6, s6, 0x80
	s_add_i32 s56, s45, 0xf0
	s_addk_i32 s6, 0xff80
	v_lshlrev_b32_e32 v16, 12, v210
	s_ashr_i32 s57, s56, 8
	s_lshr_b32 s58, s6, 6
	v_lshlrev_b64 v[92:93], 1, v[90:91]
	s_mov_b64 s[78:79], 0x40000
	s_movk_i32 s84, 0x121
	s_cmp_gt_i32 s58, s57
	v_lshl_add_u64 v[98:99], v[32:33], 0, v[92:93]
	v_lshlrev_b32_e32 v96, 1, v16
	v_lshlrev_b32_e32 v94, 13, v210
	s_cbranch_scc1 .LBB0_622
	v_add_co_u32_e32 v20, vcc, 0xc00000, v98
	v_readlane_b32 s7, v255, 47
	s_nop 0
	v_addc_co_u32_e32 v21, vcc, 0, v99, vcc
	global_load_dwordx4 v[16:19], v[20:21], off
	s_nop 0
	global_load_dwordx4 v[20:23], v[20:21], off offset:64
	v_lshl_or_b32 v136, v210, 9, s7
	v_readlane_b32 s10, v255, 48
	v_lshl_add_u64 v[24:25], s[38:39], 0, v[136:137]
	s_mov_b64 s[8:9], 0xc00000
	v_mov_b32_e32 v97, v137
	v_readlane_b32 s11, v255, 49
	v_lshl_add_u64 v[100:101], v[24:25], 0, s[8:9]
	v_lshl_add_u64 v[24:25], s[52:53], 0, v[96:97]
	s_mov_b32 s11, s93
	s_mov_b32 s12, s10
	v_writelane_b32 v255, s12, 48
	v_lshl_add_u64 v[24:25], v[24:25], 0, s[10:11]
	v_lshl_add_u64 v[24:25], v[24:25], 0, v[208:209]
	v_writelane_b32 v255, s13, 49
	s_mov_b32 s41, s93
	s_lshr_b32 s92, s6, 6
	v_lshl_add_u64 v[102:103], v[24:25], 0, s[8:9]
	s_and_b32 s54, s6, 0xffffffc0
	s_lshl_b64 s[8:9], s[40:41], 19
	s_lshl_b64 s[6:7], s[92:93], 7
	v_readlane_b32 s10, v255, 44
	s_add_u32 s6, s10, s6
	v_readlane_b32 s10, v255, 45
	s_addc_u32 s7, s10, s7
	s_add_u32 s6, s6, s8
	v_mov_b32_e32 v95, v137
	s_addc_u32 s7, s7, s9
	v_lshl_add_u64 v[104:105], s[6:7], 0, v[94:95]
	s_lshl_b64 s[6:7], s[92:93], 15
	s_add_u32 s6, s8, s6
	v_ashrrev_i32_e32 v26, 2, v88
	v_lshlrev_b32_e32 v24, 2, v112
	s_addc_u32 s7, s9, s7
	v_add_u32_e32 v25, s54, v24
	v_sub_u32_e32 v24, v26, v24
	s_add_u32 s6, s74, s6
	v_subrev_u32_e32 v24, s54, v24
	s_addc_u32 s7, s75, s7
	v_sub_u32_e32 v97, v25, v26
	v_add_u32_e32 v116, 0xffffff9d, v24
	v_lshl_add_u64 v[106:107], s[6:7], 0, v[136:137]
	s_mov_b32 s92, s58
	s_branch .LBB0_620

.LBB0_623:
	s_ashr_i32 s6, s45, 4
	s_max_i32 s8, s6, 0x80
	s_addk_i32 s8, 0xff80
	s_ashr_i32 s54, s56, 10
	s_lshr_b32 s45, s8, 6
	s_cmp_le_i32 s45, s54
	s_mov_b64 s[6:7], -1
	s_cbranch_scc0 .LBB0_629
	v_mov_b32_e32 v232, 0x4000
	v_add_co_u32_e32 v16, vcc, 0x1800000, v98
	s_and_b32 s7, s44, 15
	s_nop 0
	v_addc_co_u32_e32 v17, vcc, 0, v99, vcc
	global_load_dwordx4 v[32:35], v[16:17], off
	global_load_dwordx4 v[36:39], v[16:17], off offset:64
	v_lshl_or_b32 v16, v210, 4, s7
	v_lshlrev_b32_e32 v136, 7, v16
	v_lshl_add_u64 v[16:17], s[38:39], 0, v[136:137]
	s_mov_b64 s[10:11], 0x1800000
	v_mov_b32_e32 v97, v137
	v_lshl_add_u64 v[48:49], v[16:17], 0, s[10:11]
	v_lshl_add_u64 v[16:17], s[52:53], 0, v[96:97]
	s_lshl_b32 s92, s7, 9
	v_lshl_add_u64 v[16:17], v[16:17], 0, s[92:93]
	s_add_i32 s72, s72, s73
	v_lshl_add_u64 v[16:17], v[16:17], 0, v[208:209]
	s_mov_b32 s41, s93
	s_and_b32 s9, s72, 15
	s_lshr_b32 s92, s8, 6
	v_lshl_add_u64 v[50:51], v[16:17], 0, s[10:11]
	s_and_b32 s6, s8, 0xffffffc0
	s_lshl_b64 s[10:11], s[40:41], 19
	s_lshl_b32 s12, s9, 9
	s_lshl_b64 s[8:9], s[92:93], 7
	s_add_u32 s8, s74, s8
	s_addc_u32 s9, s75, s9
	s_add_u32 s8, s8, s12
	s_addc_u32 s9, s9, 0
	s_add_u32 s8, s8, s10
	v_mov_b32_e32 v95, v137
	s_addc_u32 s9, s9, s11
	v_lshlrev_b32_e32 v116, 2, v112
	v_lshl_add_u64 v[52:53], s[8:9], 0, v[94:95]
	s_lshl_b64 s[8:9], s[92:93], 17
	v_ashrrev_i32_e32 v18, 4, v88
	v_add_u32_e32 v16, s6, v116
	s_add_u32 s8, s10, s8
	v_sub_u32_e32 v64, v16, v18
	v_sub_u32_e32 v16, v18, v116
	s_addc_u32 s9, s11, s9
	s_lshl_b32 s7, s7, 7
	v_subrev_u32_e32 v16, s6, v16
	s_add_u32 s8, s74, s8
	v_add_u32_e32 v65, 0xffffff9d, v16
	v_lshl_or_b32 v136, v210, 11, s7
	s_addc_u32 s9, s75, s9
	v_mov_b64_e32 v[30:31], v[10:11]
	v_mov_b64_e32 v[26:27], v[14:15]
	v_mov_b64_e32 v[22:23], v[6:7]
	v_mov_b64_e32 v[18:19], v[2:3]
	v_lshl_add_u64 v[54:55], s[8:9], 0, v[136:137]
	s_mov_b32 s92, s45
	v_mov_b32_e32 v40, v114
	v_mov_b64_e32 v[28:29], v[8:9]
	v_mov_b64_e32 v[24:25], v[12:13]
	v_mov_b64_e32 v[20:21], v[4:5]
	v_mov_b64_e32 v[16:17], v[0:1]
	s_branch .LBB0_626
